# k55: k42 + unit-completion counter, its value prefetched alongside the side barrier's arrival atomic (leader spins only if the prefetched count is short)
# speedup vs baseline: 1.0005x; 1.0005x over previous
; __device__ __forceinline__ unsigned xb_add(unsigned* p, unsigned v) { return __hip_atomic_fetch_add(p, v, __ATOMIC_RELAXED, __HIP_MEMORY_SCOPE_AGENT); }
; __device__ __forceinline__ void xcd_barrier(const XcdBarrier& b) {
;     ...
;     if (threadIdx.x == 0) {
;         unsigned* bar = b.bar;
;         __builtin_amdgcn_s_waitcnt(0);
;         unsigned nloc = b.st[0], nx = b.st[1];
;         if (nloc == 0u) { xcd_barrier_complete(bar, b.x, b.gsz, nloc, nx); b.st[0] = nloc; b.st[1] = nx; }
;         const unsigned old = xb_add(&bar[XB_XSUB(b.x)], 1u);
;         const unsigned gen = old / nloc;
;         if (old + 1u == (gen + 1u) * nloc) {
.LBB0_170:
	s_mov_b64 s[6:7], exec
	s_lshl_b32 s4, s10, 8
	v_mbcnt_lo_u32_b32 v1, s6, 0
	s_add_u32 s4, s48, s4
	v_readlane_b32 s5, v251, 27
	v_mbcnt_hi_u32_b32 v1, s7, v1
	s_addc_u32 s5, s5, 0
	v_cmp_eq_u32_e32 vcc, 0, v1
	s_and_saveexec_b64 s[8:9], vcc
	s_cbranch_execz .LBB0_172
	s_bcnt1_i32_b64 s6, s[6:7]
	v_mov_b32_e32 v4, s6
	global_atomic_add v4, v208, v4, s[4:5] offset:1024 sc0
	s_mov_b32 s43, 0
	s_cmp_eq_u32 s3, 4
	s_cbranch_scc1 .Lcp_l0
	s_cmp_eq_u32 s3, 13
	s_cbranch_scc0 .Lcp_done
	s_movk_i32 s43, 0x200
	s_add_u32 s44, s94, 0x8040
	s_branch .Lcp_go
.Lcp_l0:
	s_movk_i32 s43, 0x100
	s_add_u32 s44, s94, 0x8000
.Lcp_go:
	s_addc_u32 s45, s95, 0
	global_load_dword v9, v3, s[44:45] sc1
.Lcp_done:
.LBB0_172:
	s_or_b64 exec, exec, s[8:9]
	v_cvt_f32_u32_e32 v5, v2
	s_waitcnt vmcnt(0)
	v_readfirstlane_b32 s6, v4
	v_sub_u32_e32 v4, 0, v2
	v_rcp_iflag_f32_e32 v5, v5
	v_add_u32_e32 v6, s6, v1
	v_mul_f32_e32 v5, 0x4f7ffffe, v5
	v_cvt_u32_f32_e32 v5, v5
	v_mul_lo_u32 v1, v4, v5
	v_mul_hi_u32 v1, v5, v1
	v_add_u32_e32 v1, v5, v1
	v_mul_hi_u32 v1, v6, v1
	v_mul_lo_u32 v4, v1, v2
	v_sub_u32_e32 v4, v6, v4
	v_add_u32_e32 v5, 1, v1
	v_sub_u32_e32 v7, v4, v2
	v_cmp_ge_u32_e32 vcc, v4, v2
	s_nop 1
	v_cndmask_b32_e32 v1, v1, v5, vcc
	v_cndmask_b32_e32 v4, v4, v7, vcc
	v_add_u32_e32 v5, 1, v1
	v_cmp_ge_u32_e32 vcc, v4, v2
	v_add_u32_e32 v4, 1, v6
	s_nop 0
	v_cndmask_b32_e32 v1, v1, v5, vcc
	v_mul_lo_u32 v5, v2, v1
	v_add_u32_e32 v2, v5, v2
	v_cmp_ne_u32_e32 vcc, v4, v2
	s_and_saveexec_b64 s[6:7], vcc
	s_xor_b64 s[6:7], exec, s[6:7]
	s_cbranch_execz .LBB0_186
	s_waitcnt lgkmcnt(0)
	buffer_inv sc1
	global_load_dword v0, v209, s[4:5] offset:1024 sc1
	s_add_u32 s10, s4, 0x2400
	s_addc_u32 s11, s5, 0
	s_waitcnt vmcnt(0)
	v_cmp_eq_u32_e32 vcc, v0, v1
	s_and_saveexec_b64 s[8:9], vcc
	s_cbranch_execz .LBB0_185
	s_mov_b32 s26, 1
	s_mov_b64 s[12:13], 0
	s_branch .LBB0_176

; __device__ __forceinline__ unsigned xb_add(unsigned* p, unsigned v) { return __hip_atomic_fetch_add(p, v, __ATOMIC_RELAXED, __HIP_MEMORY_SCOPE_AGENT); }
; __device__ __forceinline__ void xcd_barrier(const XcdBarrier& b) {
;     ...
;         if (old + 1u == (gen + 1u) * nloc) {
;             __builtin_amdgcn_fence(__ATOMIC_RELEASE, "agent");
;             asm volatile("s_waitcnt vmcnt(0)" ::: "memory");
;             const unsigned og = xb_add(&bar[XB_TOP], 1u);
.LBB0_186:
	s_andn2_saveexec_b64 s[6:7], s[6:7]
	s_cbranch_execz .LBB0_206
	s_mov_b64 s[6:7], exec
	s_cmp_eq_u32 s43, 0
	s_cbranch_scc1 .Lcw_done
	v_cmp_le_u32_e32 vcc, s43, v9
	s_cbranch_vccnz .Lcw_done
	s_mov_b32 s9, 0
.Lcw_spin:
	global_load_dword v9, v3, s[44:45] sc1
	s_waitcnt vmcnt(0)
	v_cmp_le_u32_e32 vcc, s43, v9
	s_cbranch_vccnz .Lcw_done
	s_sleep 1
	s_add_i32 s9, s9, 1
	s_cmp_lt_u32 s9, 0x1000
	s_cbranch_scc1 .Lcw_spin
